# dn_chunk: final u/w stores and qd/kdT outputs transposed through LDS into 16-byte stores
# speedup vs baseline: 1.0106x; 1.0106x over previous
.LBB0_290:
	s_or_b64 exec, exec, s[0:1]
	v_and_b32_e32 v35, 15, v118
	v_and_b32_e32 v176, 48, v118
	v_mad_u32_u24 v39, v35, s66, v176
	s_barrier
	ds_read_b128 v[0:3], v39 offset:32768
	v_ashrrev_i32_e32 v38, 6, v118
	v_lshl_or_b32 v32, v38, 4, v35
	v_mul_lo_u32 v36, v32, s66
	v_and_b32_e32 v37, 48, v239
	v_add_u32_e32 v33, v36, v37
	ds_read_b128 v[12:15], v33 offset:50176
	ds_read_b128 v[16:19], v33 offset:32768
	ds_read_b128 v[4:7], v33 offset:32832
	v_lshlrev_b32_e32 v20, 2, v32
	v_add_u32_e32 v8, 0x10900, v20
	v_add_u32_e32 v20, 0x10800, v20
	ds_read_b128 v[40:43], v39 offset:32832
	ds_read_b32 v34, v8
	ds_read_b32 v58, v20
	ds_read_b128 v[20:23], v33 offset:50240
	ds_read_b128 v[48:51], v39 offset:32896
	s_waitcnt lgkmcnt(6)
	v_mfma_f32_16x16x32_bf16 v[8:11], v[0:3], v[16:19], 0
	v_lshrrev_b32_e32 v56, 4, v239
	v_lshlrev_b32_e32 v59, 2, v56
	v_or_b32_e32 v61, 2, v59
	v_mfma_f32_16x16x32_bf16 v[44:47], v[0:3], v[12:15], 0
	v_or_b32_e32 v62, 3, v59
	v_lshlrev_b32_e32 v116, 3, v56
	v_lshlrev_b32_e32 v56, 4, v32
	s_waitcnt lgkmcnt(4)
	v_mfma_f32_16x16x32_bf16 v[52:55], v[40:43], v[4:7], v[8:11]
	ds_read_b128 v[28:31], v33 offset:32896
	s_nop 1
	ds_read_b128 v[8:11], v33 offset:32960
	ds_read_b128 v[24:27], v33 offset:50304
	ds_read_b128 v[0:3], v33 offset:50368
	v_sub_u32_e32 v36, v36, v56
	v_add_u32_e32 v60, v36, v37
	s_waitcnt lgkmcnt(5)
	v_mfma_f32_16x16x32_bf16 v[40:43], v[40:43], v[20:23], v[44:47]
	v_or_b32_e32 v36, 0x10800, v37
	v_ashrrev_i32_e32 v33, 31, v32
	v_cmp_gt_i32_e64 s[4:5], v32, v62
	s_waitcnt lgkmcnt(3)
	v_mfma_f32_16x16x32_bf16 v[44:47], v[48:51], v[28:31], v[52:55]
	s_ashr_i32 s47, s46, 31
	s_lshl_b64 s[0:1], s[46:47], 13
	v_cmp_ge_i32_e64 s[6:7], v32, v59
	s_waitcnt lgkmcnt(1)
	v_mfma_f32_16x16x32_bf16 v[40:43], v[48:51], v[24:27], v[40:43]
	v_lshl_add_u32 v50, v61, 2, v237
	ds_read_b32 v50, v50
	ds_read_b128 v[52:55], v39 offset:32960
	ds_read_b64 v[48:49], v36
	v_lshl_add_u32 v51, v62, 2, v237
	ds_read_b32 v51, v51
	s_waitcnt lgkmcnt(3)
	v_sub_f32_e32 v50, v58, v50
	v_min_f32_e32 v50, 0, v50
	v_mul_f32_e32 v50, 0x3fb8aa3b, v50
	v_exp_f32_e32 v56, v50
	s_waitcnt lgkmcnt(0)
	v_sub_f32_e32 v50, v58, v51
	v_min_f32_e32 v50, 0, v50
	v_lshlrev_b64 v[36:37], 7, v[32:33]
	v_mfma_f32_16x16x32_bf16 v[44:47], v[52:55], v[8:11], v[44:47]
	v_sub_f32_e32 v33, v58, v48
	v_sub_f32_e32 v49, v58, v49
	v_mul_f32_e32 v50, 0x3fb8aa3b, v50
	v_min_f32_e32 v33, 0, v33
	v_min_f32_e32 v49, 0, v49
	v_exp_f32_e32 v57, v50
	v_mul_f32_e32 v33, 0x3fb8aa3b, v33
	v_mul_f32_e32 v49, 0x3fb8aa3b, v49
	v_exp_f32_e32 v48, v33
	v_exp_f32_e32 v49, v49
	v_pk_mul_f32 v[46:47], v[34:35], v[46:47] op_sel_hi:[0,1]
	v_pk_mul_f32 v[46:47], v[46:47], v[56:57]
	v_or_b32_e32 v33, 1, v59
	v_pk_mul_f32 v[44:45], v[34:35], v[44:45] op_sel_hi:[0,1]
	v_cndmask_b32_e64 v47, 0, v47, s[4:5]
	v_cmp_gt_i32_e64 s[4:5], v32, v61
	v_pk_mul_f32 v[44:45], v[44:45], v[48:49]
	v_mfma_f32_16x16x32_bf16 v[40:43], v[52:55], v[0:3], v[40:43]
	v_cndmask_b32_e64 v46, 0, v46, s[4:5]
	v_cmp_gt_i32_e64 s[4:5], v32, v33
	v_mov_b32_e32 v161, v117
	s_mov_b32 s2, 1
	v_cndmask_b32_e64 v45, 0, v45, s[4:5]
	v_cmp_gt_i32_e64 s[4:5], v32, v59
	s_nop 1
	v_mul_f32_e32 v33, v40, v48
	v_mul_f32_e32 v63, v41, v49
	v_cndmask_b32_e64 v44, 0, v44, s[4:5]
	ds_write_b128 v60, v[44:47]
	ds_read_b128 v[44:47], v39 offset:37120
	ds_read_b128 v[48:51], v39 offset:37184
	s_waitcnt lgkmcnt(1)
	v_mfma_f32_16x16x32_bf16 v[52:55], v[44:47], v[16:19], 0
	v_mul_f32_e32 v64, v42, v56
	v_mul_f32_e32 v57, v43, v57
	v_cvt_pk_bf16_f32 v33, v33, s0
	v_mfma_f32_16x16x32_bf16 v[40:43], v[44:47], v[12:15], 0
	ds_read_b128 v[44:47], v39 offset:37248
	v_cvt_pk_bf16_f32 v56, v63, s0
	v_cndmask_b32_e64 v33, 0, v33, s[6:7]
	s_waitcnt lgkmcnt(1)
	v_mfma_f32_16x16x32_bf16 v[52:55], v[48:51], v[4:7], v[52:55]
	v_cndmask_b32_e64 v56, 0, v56, s[4:5]
	v_perm_b32 v56, v56, v33, s70
	v_cvt_pk_bf16_f32 v33, v64, s0
	v_mfma_f32_16x16x32_bf16 v[40:43], v[48:51], v[20:23], v[40:43]
	ds_read_b128 v[48:51], v39 offset:37312
	v_cmp_ge_i32_e64 s[4:5], v32, v61
	v_cvt_pk_bf16_f32 v57, v57, s0
	s_waitcnt lgkmcnt(1)
	v_mfma_f32_16x16x32_bf16 v[52:55], v[44:47], v[28:31], v[52:55]
	v_cndmask_b32_e64 v33, 0, v33, s[4:5]
	v_cmp_ge_i32_e64 s[4:5], v32, v62
	v_or_b32_e32 v62, 35, v59
	v_mfma_f32_16x16x32_bf16 v[40:43], v[44:47], v[24:27], v[40:43]
	v_cndmask_b32_e64 v57, 0, v57, s[4:5]
	s_add_u32 s4, s53, s0
	s_addc_u32 s5, s54, s1
	s_waitcnt lgkmcnt(0)
	v_mfma_f32_16x16x32_bf16 v[44:47], v[48:51], v[8:11], v[52:55]
	v_perm_b32 v57, v57, v33, s70
	v_or_b32_e32 v33, 17, v59
	v_or_b32_e32 v63, 34, v59
	v_lshl_add_u64 v[52:53], s[4:5], 0, v[36:37]
	v_lshl_add_u64 v[52:53], v[52:53], 0, v[116:117]
	global_store_dwordx2 v[52:53], v[56:57], off
	v_or_b32_e32 v52, 16, v59
	v_or_b32_e32 v57, 19, v59
	v_or_b32_e32 v53, 18, v59
	v_mfma_f32_16x16x32_bf16 v[40:43], v[48:51], v[0:3], v[40:43]
	v_lshl_add_u32 v48, v52, 2, v237
	v_lshl_add_u32 v49, v33, 2, v237
	v_lshl_add_u32 v50, v53, 2, v237
	v_lshl_add_u32 v51, v57, 2, v237
	ds_read_b32 v48, v48
	ds_read_b32 v49, v49
	ds_read_b32 v50, v50
	ds_read_b32 v51, v51
	v_pk_mul_f32 v[46:47], v[34:35], v[46:47] op_sel_hi:[0,1]
	v_cmp_gt_i32_e64 s[4:5], v32, v57
	s_waitcnt lgkmcnt(2)
	v_sub_f32_e32 v49, v58, v49
	s_waitcnt lgkmcnt(1)
	v_sub_f32_e32 v50, v58, v50
	s_waitcnt lgkmcnt(0)
	v_sub_f32_e32 v51, v58, v51
	v_min_f32_e32 v50, 0, v50
	v_min_f32_e32 v51, 0, v51
	v_sub_f32_e32 v48, v58, v48
	v_mul_f32_e32 v50, 0x3fb8aa3b, v50
	v_mul_f32_e32 v51, 0x3fb8aa3b, v51
	v_min_f32_e32 v48, 0, v48
	v_min_f32_e32 v49, 0, v49
	v_exp_f32_e32 v50, v50
	v_exp_f32_e32 v51, v51
	v_mul_f32_e32 v48, 0x3fb8aa3b, v48
	v_mul_f32_e32 v49, 0x3fb8aa3b, v49
	v_exp_f32_e32 v48, v48
	v_exp_f32_e32 v49, v49
	v_pk_mul_f32 v[46:47], v[46:47], v[50:51]
	v_pk_mul_f32 v[44:45], v[34:35], v[44:45] op_sel_hi:[0,1]
	v_cndmask_b32_e64 v47, 0, v47, s[4:5]
	v_cmp_gt_i32_e64 s[4:5], v32, v53
	v_pk_mul_f32 v[44:45], v[44:45], v[48:49]
	v_mul_f32_e32 v40, v40, v48
	v_cndmask_b32_e64 v46, 0, v46, s[4:5]
	v_cmp_gt_i32_e64 s[4:5], v32, v33
	v_mul_f32_e32 v41, v41, v49
	v_cvt_pk_bf16_f32 v40, v40, s0
	v_cndmask_b32_e64 v45, 0, v45, s[4:5]
	v_cmp_gt_i32_e64 s[4:5], v32, v52
	v_mul_f32_e32 v54, v42, v50
	v_mul_f32_e32 v55, v43, v51
	v_cndmask_b32_e64 v44, 0, v44, s[4:5]
	ds_write_b128 v60, v[44:47] offset:64
	ds_read_b128 v[44:47], v39 offset:41472
	v_cmp_ge_i32_e64 s[4:5], v32, v52
	v_cvt_pk_bf16_f32 v56, v41, s0
	v_cvt_pk_bf16_f32 v61, v55, s0
	v_cndmask_b32_e64 v52, 0, v40, s[4:5]
	ds_read_b128 v[40:43], v39 offset:41536
	v_cmp_ge_i32_e64 s[4:5], v32, v33
	s_waitcnt lgkmcnt(1)
	v_mfma_f32_16x16x32_bf16 v[48:51], v[44:47], v[16:19], 0
	v_cndmask_b32_e64 v33, 0, v56, s[4:5]
	v_perm_b32 v56, v33, v52, s70
	v_cvt_pk_bf16_f32 v33, v54, s0
	v_cmp_ge_i32_e64 s[4:5], v32, v53
	ds_read_b128 v[52:55], v39 offset:41600
	v_mfma_f32_16x16x32_bf16 v[44:47], v[44:47], v[12:15], 0
	v_cndmask_b32_e64 v33, 0, v33, s[4:5]
	v_cmp_ge_i32_e64 s[4:5], v32, v57
	s_add_u32 s0, s92, s0
	s_waitcnt lgkmcnt(1)
	v_mfma_f32_16x16x32_bf16 v[48:51], v[40:43], v[4:7], v[48:51]
	v_cndmask_b32_e64 v57, 0, v61, s[4:5]
	v_perm_b32 v57, v57, v33, s70
	v_or_b32_e32 v33, 33, v59
	v_mfma_f32_16x16x32_bf16 v[40:43], v[40:43], v[20:23], v[44:47]
	v_or_b32_e32 v61, 32, v59
	s_addc_u32 s1, s93, s1
	v_lshl_add_u64 v[36:37], s[0:1], 0, v[36:37]
	ds_read_b128 v[44:47], v39 offset:41664
	s_waitcnt lgkmcnt(1)
	v_mfma_f32_16x16x32_bf16 v[48:51], v[52:55], v[28:31], v[48:51]
	v_lshl_add_u64 v[36:37], v[36:37], 0, v[116:117]
	v_add_co_u32_e64 v36, s[4:5], s71, v36
	v_mfma_f32_16x16x32_bf16 v[40:43], v[52:55], v[24:27], v[40:43]
	v_lshl_add_u32 v52, v61, 2, v237
	v_lshl_add_u32 v53, v33, 2, v237
	v_lshl_add_u32 v54, v63, 2, v237
	v_lshl_add_u32 v55, v62, 2, v237
	ds_read_b32 v52, v52
	ds_read_b32 v53, v53
	ds_read_b32 v54, v54
	ds_read_b32 v55, v55
	s_waitcnt lgkmcnt(4)
	v_mfma_f32_16x16x32_bf16 v[48:51], v[44:47], v[8:11], v[48:51]
	v_addc_co_u32_e64 v37, s[4:5], 0, v37, s[4:5]
	s_waitcnt lgkmcnt(1)
	v_sub_f32_e32 v54, v58, v54
	s_waitcnt lgkmcnt(0)
	v_sub_f32_e32 v55, v58, v55
	v_min_f32_e32 v54, 0, v54
	v_min_f32_e32 v55, 0, v55
	v_sub_f32_e32 v52, v58, v52
	v_sub_f32_e32 v53, v58, v53
	v_mul_f32_e32 v54, 0x3fb8aa3b, v54
	v_mul_f32_e32 v55, 0x3fb8aa3b, v55
	v_min_f32_e32 v52, 0, v52
	v_min_f32_e32 v53, 0, v53
	v_exp_f32_e32 v54, v54
	v_exp_f32_e32 v55, v55
	v_mul_f32_e32 v52, 0x3fb8aa3b, v52
	v_mul_f32_e32 v53, 0x3fb8aa3b, v53
	v_exp_f32_e32 v52, v52
	v_exp_f32_e32 v53, v53
	v_pk_mul_f32 v[50:51], v[34:35], v[50:51] op_sel_hi:[0,1]
	v_pk_mul_f32 v[50:51], v[50:51], v[54:55]
	v_cmp_gt_i32_e64 s[4:5], v32, v62
	v_pk_mul_f32 v[48:49], v[34:35], v[48:49] op_sel_hi:[0,1]
	v_pk_mul_f32 v[48:49], v[48:49], v[52:53]
	v_cndmask_b32_e64 v51, 0, v51, s[4:5]
	v_cmp_gt_i32_e64 s[4:5], v32, v63
	v_mfma_f32_16x16x32_bf16 v[40:43], v[44:47], v[0:3], v[40:43]
	global_store_dwordx2 v[36:37], v[56:57], off offset:32
	v_cndmask_b32_e64 v50, 0, v50, s[4:5]
	v_cmp_gt_i32_e64 s[4:5], v32, v33
	s_mov_b32 s3, 0
	s_mov_b32 s6, 32
	v_cndmask_b32_e64 v49, 0, v49, s[4:5]
	v_cmp_gt_i32_e64 s[4:5], v32, v61
	s_nop 0
	v_mul_f32_e32 v40, v40, v52
	v_cvt_pk_bf16_f32 v40, v40, s0
	v_cndmask_b32_e64 v48, 0, v48, s[4:5]
	ds_write_b128 v60, v[48:51] offset:128
	ds_read_b128 v[48:51], v39 offset:45824
	ds_read_b128 v[44:47], v39 offset:45888
	s_waitcnt lgkmcnt(1)
	v_mfma_f32_16x16x32_bf16 v[16:19], v[48:51], v[16:19], 0
	v_cmp_ge_i32_e64 s[4:5], v32, v61
	v_mul_f32_e32 v52, v41, v53
	v_mul_f32_e32 v53, v42, v54
	v_mul_f32_e32 v54, v43, v55
	v_mfma_f32_16x16x32_bf16 v[12:15], v[48:51], v[12:15], 0
	v_cndmask_b32_e64 v48, 0, v40, s[4:5]
	ds_read_b128 v[40:43], v39 offset:45952
	v_cmp_ge_i32_e64 s[4:5], v32, v33
	s_waitcnt lgkmcnt(1)
	v_mfma_f32_16x16x32_bf16 v[4:7], v[44:47], v[4:7], v[16:19]
	s_nop 2
	v_cvt_pk_bf16_f32 v16, v52, s0
	v_cndmask_b32_e64 v16, 0, v16, s[4:5]
	v_mfma_f32_16x16x32_bf16 v[12:15], v[44:47], v[20:23], v[12:15]
	v_perm_b32 v20, v16, v48, s70
	ds_read_b128 v[16:19], v39 offset:46016
	v_cvt_pk_bf16_f32 v21, v53, s0
	s_waitcnt lgkmcnt(1)
	v_mfma_f32_16x16x32_bf16 v[4:7], v[40:43], v[28:31], v[4:7]
	v_cmp_ge_i32_e64 s[4:5], v32, v63
	v_cvt_pk_bf16_f32 v22, v54, s0
	s_nop 0
	v_cndmask_b32_e64 v21, 0, v21, s[4:5]
	v_cmp_ge_i32_e64 s[4:5], v32, v62
	s_waitcnt lgkmcnt(0)
	v_mfma_f32_16x16x32_bf16 v[4:7], v[16:19], v[8:11], v[4:7]
	v_cndmask_b32_e64 v22, 0, v22, s[4:5]
	v_or_b32_e32 v11, 48, v59
	v_perm_b32 v21, v22, v21, s70
	v_lshl_add_u32 v8, v11, 2, v237
	global_store_dwordx2 v[36:37], v[20:21], off offset:64
	v_or_b32_e32 v10, 49, v59
	ds_read_b32 v8, v8
	v_or_b32_e32 v20, 51, v59
	v_or_b32_e32 v21, 50, v59
	v_lshl_add_u32 v9, v10, 2, v237
	v_lshl_add_u32 v22, v21, 2, v237
	v_lshl_add_u32 v23, v20, 2, v237
	ds_read_b32 v9, v9
	ds_read_b32 v22, v22
	ds_read_b32 v23, v23
	v_mfma_f32_16x16x32_bf16 v[12:15], v[40:43], v[24:27], v[12:15]
	s_waitcnt lgkmcnt(3)
	v_sub_f32_e32 v8, v58, v8
	s_waitcnt lgkmcnt(2)
	v_sub_f32_e32 v9, v58, v9
	v_min_f32_e32 v8, 0, v8
	v_min_f32_e32 v9, 0, v9
	v_mul_f32_e32 v8, 0x3fb8aa3b, v8
	v_mul_f32_e32 v9, 0x3fb8aa3b, v9
	v_exp_f32_e32 v8, v8
	v_exp_f32_e32 v9, v9
	v_mfma_f32_16x16x32_bf16 v[0:3], v[16:19], v[0:3], v[12:15]
	v_mul_f32_e64 v6, v34, v6
	v_mul_f32_e64 v7, v34, v7
	v_cmp_gt_i32_e64 s[4:5], v32, v20
	v_pk_mul_f32 v[4:5], v[34:35], v[4:5] op_sel_hi:[0,1]
	v_pk_mul_f32 v[4:5], v[4:5], v[8:9]
	s_nop 2
	v_mul_f32_e32 v12, v0, v8
	v_mul_f32_e32 v13, v1, v9
	s_waitcnt lgkmcnt(1)
	v_sub_f32_e32 v0, v58, v22
	s_waitcnt lgkmcnt(0)
	v_sub_f32_e32 v1, v58, v23
	v_min_f32_e32 v0, 0, v0
	v_min_f32_e32 v1, 0, v1
	v_mul_f32_e32 v0, 0x3fb8aa3b, v0
	v_mul_f32_e32 v1, 0x3fb8aa3b, v1
	v_exp_f32_e32 v0, v0
	v_exp_f32_e32 v1, v1
	v_mul_f32_e32 v2, v2, v0
	v_pk_mul_f32 v[6:7], v[6:7], v[0:1]
	v_cvt_pk_bf16_f32 v0, v12, s0
	v_cndmask_b32_e64 v7, 0, v7, s[4:5]
	v_cmp_gt_i32_e64 s[4:5], v32, v21
	v_mul_f32_e32 v1, v3, v1
	v_cvt_pk_bf16_f32 v3, v13, s0
	v_cndmask_b32_e64 v6, 0, v6, s[4:5]
	v_cmp_gt_i32_e64 s[4:5], v32, v10
	v_cvt_pk_bf16_f32 v2, v2, s0
	v_cvt_pk_bf16_f32 v1, v1, s0
	v_cndmask_b32_e64 v5, 0, v5, s[4:5]
	v_cmp_gt_i32_e64 s[4:5], v32, v11
	s_lshl_b64 s[0:1], s[46:47], 14
	s_nop 0
	v_cndmask_b32_e64 v4, 0, v4, s[4:5]
	v_cmp_ge_i32_e64 s[4:5], v32, v11
	ds_write_b128 v60, v[4:7] offset:192
	s_nop 0
	v_cndmask_b32_e64 v0, 0, v0, s[4:5]
	v_cmp_ge_i32_e64 s[4:5], v32, v10
	s_nop 1
	v_cndmask_b32_e64 v3, 0, v3, s[4:5]
	v_cmp_ge_i32_e64 s[4:5], v32, v21
	v_perm_b32 v0, v3, v0, s70
	s_nop 0
	v_cndmask_b32_e64 v2, 0, v2, s[4:5]
	v_cmp_ge_i32_e64 s[4:5], v32, v20
	s_nop 1
	v_cndmask_b32_e64 v1, 0, v1, s[4:5]
	s_add_u32 s4, s55, s0
	v_perm_b32 v1, v1, v2, s70
	s_addc_u32 s5, s56, s1
	global_store_dwordx2 v[36:37], v[0:1], off offset:96
	v_lshl_add_u64 v[0:1], s[4:5], 0, v[160:161]
	s_waitcnt lgkmcnt(0)
	s_barrier
	s_lshl_b32 s6, s46, 14
	s_add_u32 s2, s92, s6
	s_addc_u32 s3, s93, 0
	s_add_u32 s4, s2, 0x2a000000
	s_addc_u32 s5, s3, 0
	s_add_u32 s2, s2, 0x26000000
	s_addc_u32 s3, s3, 0
	v_lshrrev_b32_e32 v0, 2, v208
	v_and_b32_e32 v1, 3, v208
	v_mul_u32_u24_e32 v2, 0x110, v0
	v_lshl_add_u32 v2, v1, 6, v2
	v_lshlrev_b32_e32 v34, 2, v0
	v_add_u32_e32 v34, 0x10b00, v34
	ds_read_b128 v[8:11], v2 offset:50176
	ds_read_b128 v[12:15], v2 offset:50192
	ds_read_b128 v[16:19], v2 offset:50208
	ds_read_b128 v[20:23], v2 offset:50224
	ds_read_b32 v4, v34
	v_and_b32_e32 v5, 63, v208
	v_lshrrev_b32_e32 v6, 6, v208
	v_mul_u32_u24_e32 v7, 0x110, v5
	v_lshl_add_u32 v7, v6, 6, v7
	ds_read_b128 v[24:27], v7 offset:32768
	ds_read_b128 v[28:31], v7 offset:32784
	ds_read_b128 v[40:43], v7 offset:32800
	ds_read_b128 v[44:47], v7 offset:32816
	v_lshlrev_b32_e32 v32, 2, v5
	v_add_u32_e32 v32, 0x10800, v32
	ds_read_b32 v33, v32
	v_mov_b32_e32 v53, 0x108fc
	ds_read_b32 v3, v53
	v_lshlrev_b32_e32 v36, 8, v0
	v_lshl_add_u32 v36, v1, 6, v36
	v_lshlrev_b32_e32 v37, 12, v6
	v_lshl_add_u32 v39, v5, 1, v37
	v_lshrrev_b32_e32 v51, 3, v5
	v_and_b32_e32 v52, 7, v5
	v_lshlrev_b32_e32 v52, 4, v52
	v_lshl_add_u32 v51, v51, 7, v52
	v_add_u32_e32 v51, v51, v37
	s_waitcnt lgkmcnt(0)
	v_lshlrev_b32_e32 v49, 16, v8
	v_and_b32_e32 v50, 0xffff0000, v8
	v_mul_f32_e32 v49, v4, v49
	v_mul_f32_e32 v50, v4, v50
	v_cvt_pk_bf16_f32 v8, v49, v50
	v_lshlrev_b32_e32 v49, 16, v9
	v_and_b32_e32 v50, 0xffff0000, v9
	v_mul_f32_e32 v49, v4, v49
	v_mul_f32_e32 v50, v4, v50
	v_cvt_pk_bf16_f32 v9, v49, v50
	v_lshlrev_b32_e32 v49, 16, v10
	v_and_b32_e32 v50, 0xffff0000, v10
	v_mul_f32_e32 v49, v4, v49
	v_mul_f32_e32 v50, v4, v50
	v_cvt_pk_bf16_f32 v10, v49, v50
	v_lshlrev_b32_e32 v49, 16, v11
	v_and_b32_e32 v50, 0xffff0000, v11
	v_mul_f32_e32 v49, v4, v49
	v_mul_f32_e32 v50, v4, v50
	v_cvt_pk_bf16_f32 v11, v49, v50
	v_lshlrev_b32_e32 v49, 16, v12
	v_and_b32_e32 v50, 0xffff0000, v12
	v_mul_f32_e32 v49, v4, v49
	v_mul_f32_e32 v50, v4, v50
	v_cvt_pk_bf16_f32 v12, v49, v50
	v_lshlrev_b32_e32 v49, 16, v13
	v_and_b32_e32 v50, 0xffff0000, v13
	v_mul_f32_e32 v49, v4, v49
	v_mul_f32_e32 v50, v4, v50
	v_cvt_pk_bf16_f32 v13, v49, v50
	v_lshlrev_b32_e32 v49, 16, v14
	v_and_b32_e32 v50, 0xffff0000, v14
	v_mul_f32_e32 v49, v4, v49
	v_mul_f32_e32 v50, v4, v50
	v_cvt_pk_bf16_f32 v14, v49, v50
	v_lshlrev_b32_e32 v49, 16, v15
	v_and_b32_e32 v50, 0xffff0000, v15
	v_mul_f32_e32 v49, v4, v49
	v_mul_f32_e32 v50, v4, v50
	v_cvt_pk_bf16_f32 v15, v49, v50
	v_lshlrev_b32_e32 v49, 16, v16
	v_and_b32_e32 v50, 0xffff0000, v16
	v_mul_f32_e32 v49, v4, v49
	v_mul_f32_e32 v50, v4, v50
	v_cvt_pk_bf16_f32 v16, v49, v50
	v_lshlrev_b32_e32 v49, 16, v17
	v_and_b32_e32 v50, 0xffff0000, v17
	v_mul_f32_e32 v49, v4, v49
	v_mul_f32_e32 v50, v4, v50
	v_cvt_pk_bf16_f32 v17, v49, v50
	v_lshlrev_b32_e32 v49, 16, v18
	v_and_b32_e32 v50, 0xffff0000, v18
	v_mul_f32_e32 v49, v4, v49
	v_mul_f32_e32 v50, v4, v50
	v_cvt_pk_bf16_f32 v18, v49, v50
	v_lshlrev_b32_e32 v49, 16, v19
	v_and_b32_e32 v50, 0xffff0000, v19
	v_mul_f32_e32 v49, v4, v49
	v_mul_f32_e32 v50, v4, v50
	v_cvt_pk_bf16_f32 v19, v49, v50
	v_lshlrev_b32_e32 v49, 16, v20
	v_and_b32_e32 v50, 0xffff0000, v20
	v_mul_f32_e32 v49, v4, v49
	v_mul_f32_e32 v50, v4, v50
	v_cvt_pk_bf16_f32 v20, v49, v50
	v_lshlrev_b32_e32 v49, 16, v21
	v_and_b32_e32 v50, 0xffff0000, v21
	v_mul_f32_e32 v49, v4, v49
	v_mul_f32_e32 v50, v4, v50
	v_cvt_pk_bf16_f32 v21, v49, v50
	v_lshlrev_b32_e32 v49, 16, v22
	v_and_b32_e32 v50, 0xffff0000, v22
	v_mul_f32_e32 v49, v4, v49
	v_mul_f32_e32 v50, v4, v50
	v_cvt_pk_bf16_f32 v22, v49, v50
	v_lshlrev_b32_e32 v49, 16, v23
	v_and_b32_e32 v50, 0xffff0000, v23
	v_mul_f32_e32 v49, v4, v49
	v_mul_f32_e32 v50, v4, v50
	v_cvt_pk_bf16_f32 v23, v49, v50
	global_store_dwordx4 v36, v[8:11], s[2:3]
	global_store_dwordx4 v36, v[12:15], s[2:3] offset:16
	global_store_dwordx4 v36, v[16:19], s[2:3] offset:32
	global_store_dwordx4 v36, v[20:23], s[2:3] offset:48
	v_sub_f32_e32 v48, v3, v33
	v_mul_f32_e32 v48, 0x3fb8aa3b, v48
	v_exp_f32_e32 v48, v48
	s_nop 0
	v_lshlrev_b32_e32 v49, 16, v24
	v_and_b32_e32 v50, 0xffff0000, v24
	v_mul_f32_e32 v49, v48, v49
	v_mul_f32_e32 v50, v48, v50
	v_cvt_pk_bf16_f32 v49, v49, v50
	ds_write_b16 v39, v49 offset:16384
	ds_write_b16_d16_hi v39, v49 offset:16512
	v_lshlrev_b32_e32 v49, 16, v25
	v_and_b32_e32 v50, 0xffff0000, v25
	v_mul_f32_e32 v49, v48, v49
	v_mul_f32_e32 v50, v48, v50
	v_cvt_pk_bf16_f32 v49, v49, v50
	ds_write_b16 v39, v49 offset:16640
	ds_write_b16_d16_hi v39, v49 offset:16768
	v_lshlrev_b32_e32 v49, 16, v26
	v_and_b32_e32 v50, 0xffff0000, v26
	v_mul_f32_e32 v49, v48, v49
	v_mul_f32_e32 v50, v48, v50
	v_cvt_pk_bf16_f32 v49, v49, v50
	ds_write_b16 v39, v49 offset:16896
	ds_write_b16_d16_hi v39, v49 offset:17024
	v_lshlrev_b32_e32 v49, 16, v27
	v_and_b32_e32 v50, 0xffff0000, v27
	v_mul_f32_e32 v49, v48, v49
	v_mul_f32_e32 v50, v48, v50
	v_cvt_pk_bf16_f32 v49, v49, v50
	ds_write_b16 v39, v49 offset:17152
	ds_write_b16_d16_hi v39, v49 offset:17280
	v_lshlrev_b32_e32 v49, 16, v28
	v_and_b32_e32 v50, 0xffff0000, v28
	v_mul_f32_e32 v49, v48, v49
	v_mul_f32_e32 v50, v48, v50
	v_cvt_pk_bf16_f32 v49, v49, v50
	ds_write_b16 v39, v49 offset:17408
	ds_write_b16_d16_hi v39, v49 offset:17536
	v_lshlrev_b32_e32 v49, 16, v29
	v_and_b32_e32 v50, 0xffff0000, v29
	v_mul_f32_e32 v49, v48, v49
	v_mul_f32_e32 v50, v48, v50
	v_cvt_pk_bf16_f32 v49, v49, v50
	ds_write_b16 v39, v49 offset:17664
	ds_write_b16_d16_hi v39, v49 offset:17792
	v_lshlrev_b32_e32 v49, 16, v30
	v_and_b32_e32 v50, 0xffff0000, v30
	v_mul_f32_e32 v49, v48, v49
	v_mul_f32_e32 v50, v48, v50
	v_cvt_pk_bf16_f32 v49, v49, v50
	ds_write_b16 v39, v49 offset:17920
	ds_write_b16_d16_hi v39, v49 offset:18048
	v_lshlrev_b32_e32 v49, 16, v31
	v_and_b32_e32 v50, 0xffff0000, v31
	v_mul_f32_e32 v49, v48, v49
	v_mul_f32_e32 v50, v48, v50
	v_cvt_pk_bf16_f32 v49, v49, v50
	ds_write_b16 v39, v49 offset:18176
	ds_write_b16_d16_hi v39, v49 offset:18304
	v_lshlrev_b32_e32 v49, 16, v40
	v_and_b32_e32 v50, 0xffff0000, v40
	v_mul_f32_e32 v49, v48, v49
	v_mul_f32_e32 v50, v48, v50
	v_cvt_pk_bf16_f32 v49, v49, v50
	ds_write_b16 v39, v49 offset:18432
	ds_write_b16_d16_hi v39, v49 offset:18560
	v_lshlrev_b32_e32 v49, 16, v41
	v_and_b32_e32 v50, 0xffff0000, v41
	v_mul_f32_e32 v49, v48, v49
	v_mul_f32_e32 v50, v48, v50
	v_cvt_pk_bf16_f32 v49, v49, v50
	ds_write_b16 v39, v49 offset:18688
	ds_write_b16_d16_hi v39, v49 offset:18816
	v_lshlrev_b32_e32 v49, 16, v42
	v_and_b32_e32 v50, 0xffff0000, v42
	v_mul_f32_e32 v49, v48, v49
	v_mul_f32_e32 v50, v48, v50
	v_cvt_pk_bf16_f32 v49, v49, v50
	ds_write_b16 v39, v49 offset:18944
	ds_write_b16_d16_hi v39, v49 offset:19072
	v_lshlrev_b32_e32 v49, 16, v43
	v_and_b32_e32 v50, 0xffff0000, v43
	v_mul_f32_e32 v49, v48, v49
	v_mul_f32_e32 v50, v48, v50
	v_cvt_pk_bf16_f32 v49, v49, v50
	ds_write_b16 v39, v49 offset:19200
	ds_write_b16_d16_hi v39, v49 offset:19328
	v_lshlrev_b32_e32 v49, 16, v44
	v_and_b32_e32 v50, 0xffff0000, v44
	v_mul_f32_e32 v49, v48, v49
	v_mul_f32_e32 v50, v48, v50
	v_cvt_pk_bf16_f32 v49, v49, v50
	ds_write_b16 v39, v49 offset:19456
	ds_write_b16_d16_hi v39, v49 offset:19584
	v_lshlrev_b32_e32 v49, 16, v45
	v_and_b32_e32 v50, 0xffff0000, v45
	v_mul_f32_e32 v49, v48, v49
	v_mul_f32_e32 v50, v48, v50
	v_cvt_pk_bf16_f32 v49, v49, v50
	ds_write_b16 v39, v49 offset:19712
	ds_write_b16_d16_hi v39, v49 offset:19840
	v_lshlrev_b32_e32 v49, 16, v46
	v_and_b32_e32 v50, 0xffff0000, v46
	v_mul_f32_e32 v49, v48, v49
	v_mul_f32_e32 v50, v48, v50
	v_cvt_pk_bf16_f32 v49, v49, v50
	ds_write_b16 v39, v49 offset:19968
	ds_write_b16_d16_hi v39, v49 offset:20096
	v_lshlrev_b32_e32 v49, 16, v47
	v_and_b32_e32 v50, 0xffff0000, v47
	v_mul_f32_e32 v49, v48, v49
	v_mul_f32_e32 v50, v48, v50
	v_cvt_pk_bf16_f32 v49, v49, v50
	ds_write_b16 v39, v49 offset:20224
	ds_write_b16_d16_hi v39, v49 offset:20352
	s_waitcnt lgkmcnt(0)
	ds_read_b128 v[8:11], v51 offset:16384
	ds_read_b128 v[12:15], v51 offset:17408
	ds_read_b128 v[16:19], v51 offset:18432
	ds_read_b128 v[20:23], v51 offset:19456
	s_waitcnt lgkmcnt(0)
	global_store_dwordx4 v51, v[8:11], s[4:5]
	global_store_dwordx4 v51, v[12:15], s[4:5] offset:1024
	global_store_dwordx4 v51, v[16:19], s[4:5] offset:2048
	global_store_dwordx4 v51, v[20:23], s[4:5] offset:3072
	s_nop 1
	v_cmp_eq_u32_e64 s[4:5], 0, v118
	s_and_saveexec_b64 s[2:3], s[4:5]
	s_cbranch_execz .LBB0_229
	v_mul_f32_e32 v0, 0x3fb8aa3b, v3
	v_exp_f32_e32 v0, v0
	s_lshl_b64 s[4:5], s[46:47], 2
	s_add_u32 s4, s59, s4
	s_addc_u32 s5, s60, s5
	global_store_dword v117, v0, s[4:5]
	s_branch .LBB0_229
